# baseline (speedup 1.0000x reference)
; __device__ __forceinline__ float shfl_idx(float v, int srclane) { return __int_as_float(__builtin_amdgcn_ds_bpermute(srclane << 2, __float_as_int(v))); }
; __device__ __forceinline__ int crow(int r, int hi) { return (r & 3) + 8 * (r >> 2) + 4 * hi; }
; __device__ __forceinline__ void dil_wave_item(const bf16* __restrict__ qkv, bf16* __restrict__ odil, float* __restrict__ lse,
;                               int pat, int g  , int head, char* wl  , const int W) {
;     ...
;   const float rl = __builtin_amdgcn_rcpf(ls);
; #pragma unroll
;   for (int r = 0; r < 16; ++r) {
;     const int q = crow(r, hi);
;     const float rq = shfl_idx(rl, q);
;     bf16* dst = odil + ((size_t)pat * T + tbase + (i0 + q) * dil) * 512 + head * 64 + r32;
;     dst[0] = __float2bfloat16(o0[r] * rq); dst[32] = __float2bfloat16(o1[r] * rq);
;   }
.LBB0_82:
	s_or_b64 exec, exec, s[4:5]
	v_rcp_f32_e32 v38, v35
	v_or_b32_e32 v36, s78, v91
	v_lshlrev_b32_e32 v36, s71, v36
	v_ashrrev_i32_e32 v37, 31, v36
	v_lshl_add_u64 v[36:37], v[32:33], 0, v[36:37]
	v_lshlrev_b32_e32 v34, 2, v90
	v_mov_b32_e32 v35, v83
	v_lshlrev_b64 v[36:37], 10, v[36:37]
	v_lshl_add_u64 v[34:35], s[76:77], 0, v[34:35]
	s_add_i32 s70, s70, s33
	v_lshl_add_u64 v[36:37], v[34:35], 0, v[36:37]
	v_pk_mul_f32 v[0:1], v[0:1], v[38:39] op_sel_hi:[1,0]
	v_pk_mul_f32 v[2:3], v[2:3], v[38:39] op_sel_hi:[1,0]
	v_pk_mul_f32 v[4:5], v[4:5], v[38:39] op_sel_hi:[1,0]
	v_pk_mul_f32 v[6:7], v[6:7], v[38:39] op_sel_hi:[1,0]
	v_pk_mul_f32 v[8:9], v[8:9], v[38:39] op_sel_hi:[1,0]
	v_pk_mul_f32 v[10:11], v[10:11], v[38:39] op_sel_hi:[1,0]
	v_pk_mul_f32 v[12:13], v[12:13], v[38:39] op_sel_hi:[1,0]
	v_pk_mul_f32 v[14:15], v[14:15], v[38:39] op_sel_hi:[1,0]
	v_cvt_pk_bf16_f32 v0, v0, v1
	v_cvt_pk_bf16_f32 v1, v2, v3
	v_cvt_pk_bf16_f32 v2, v4, v5
	v_cvt_pk_bf16_f32 v3, v6, v7
	v_cvt_pk_bf16_f32 v4, v8, v9
	v_cvt_pk_bf16_f32 v5, v10, v11
	v_cvt_pk_bf16_f32 v6, v12, v13
	v_cvt_pk_bf16_f32 v7, v14, v15
	s_nop 1
	v_permlane32_swap_b32_e32 v0, v2
	v_permlane32_swap_b32_e32 v1, v3
	v_permlane32_swap_b32_e32 v4, v6
	v_permlane32_swap_b32_e32 v5, v7
	global_store_dwordx4 v[36:37], v[0:3], off
	global_store_dwordx4 v[36:37], v[4:7], off offset:32
	v_pk_mul_f32 v[16:17], v[16:17], v[38:39] op_sel_hi:[1,0]
	v_pk_mul_f32 v[18:19], v[18:19], v[38:39] op_sel_hi:[1,0]
	v_pk_mul_f32 v[20:21], v[20:21], v[38:39] op_sel_hi:[1,0]
	v_pk_mul_f32 v[22:23], v[22:23], v[38:39] op_sel_hi:[1,0]
	v_pk_mul_f32 v[24:25], v[24:25], v[38:39] op_sel_hi:[1,0]
	v_pk_mul_f32 v[26:27], v[26:27], v[38:39] op_sel_hi:[1,0]
	v_pk_mul_f32 v[28:29], v[28:29], v[38:39] op_sel_hi:[1,0]
	v_pk_mul_f32 v[30:31], v[30:31], v[38:39] op_sel_hi:[1,0]
	v_cvt_pk_bf16_f32 v16, v16, v17
	v_cvt_pk_bf16_f32 v17, v18, v19
	v_cvt_pk_bf16_f32 v18, v20, v21
	v_cvt_pk_bf16_f32 v19, v22, v23
	v_cvt_pk_bf16_f32 v20, v24, v25
	v_cvt_pk_bf16_f32 v21, v26, v27
	v_cvt_pk_bf16_f32 v22, v28, v29
	v_cvt_pk_bf16_f32 v23, v30, v31
	s_nop 1
	v_permlane32_swap_b32_e32 v16, v18
	v_permlane32_swap_b32_e32 v17, v19
	v_permlane32_swap_b32_e32 v20, v22
	v_permlane32_swap_b32_e32 v21, v23
	global_store_dwordx4 v[36:37], v[16:19], off offset:64
	global_store_dwordx4 v[36:37], v[20:23], off offset:96
	s_cmpk_gt_i32 s70, 0xbff
	s_cbranch_scc1 .LBB0_94

; __device__ __forceinline__ float shfl_idx(float v, int srclane) { return __int_as_float(__builtin_amdgcn_ds_bpermute(srclane << 2, __float_as_int(v))); }
; __device__ __forceinline__ int crow(int r, int hi) { return (r & 3) + 8 * (r >> 2) + 4 * hi; }
; __device__ __forceinline__ void dil_wave_item(const bf16* __restrict__ qkv, bf16* __restrict__ odil, float* __restrict__ lse,
;                               int pat, int g  , int head, char* wl  , const int W) {
;     ...
;   const float rl = __builtin_amdgcn_rcpf(ls);
; #pragma unroll
;   for (int r = 0; r < 16; ++r) {
;     const int q = crow(r, hi);
;     const float rq = shfl_idx(rl, q);
;     bf16* dst = odil + ((size_t)pat * T + tbase + (i0 + q) * dil) * 512 + head * 64 + r32;
;     dst[0] = __float2bfloat16(o0[r] * rq); dst[32] = __float2bfloat16(o1[r] * rq);
;   }
.LBB0_293:
	s_or_b64 exec, exec, s[6:7]
	v_rcp_f32_e32 v38, v35
	v_or_b32_e32 v36, s41, v102
	v_lshlrev_b32_e32 v36, s40, v36
	v_ashrrev_i32_e32 v37, 31, v36
	v_lshl_add_u64 v[36:37], v[32:33], 0, v[36:37]
	v_lshlrev_b32_e32 v34, 2, v80
	v_mov_b32_e32 v35, v95
	v_lshlrev_b64 v[36:37], 10, v[36:37]
	v_lshl_add_u64 v[34:35], s[76:77], 0, v[34:35]
	s_add_i32 s27, s27, s33
	v_lshl_add_u64 v[36:37], v[34:35], 0, v[36:37]
	v_pk_mul_f32 v[0:1], v[0:1], v[38:39] op_sel_hi:[1,0]
	v_pk_mul_f32 v[2:3], v[2:3], v[38:39] op_sel_hi:[1,0]
	v_pk_mul_f32 v[4:5], v[4:5], v[38:39] op_sel_hi:[1,0]
	v_pk_mul_f32 v[6:7], v[6:7], v[38:39] op_sel_hi:[1,0]
	v_pk_mul_f32 v[8:9], v[8:9], v[38:39] op_sel_hi:[1,0]
	v_pk_mul_f32 v[10:11], v[10:11], v[38:39] op_sel_hi:[1,0]
	v_pk_mul_f32 v[12:13], v[12:13], v[38:39] op_sel_hi:[1,0]
	v_pk_mul_f32 v[14:15], v[14:15], v[38:39] op_sel_hi:[1,0]
	v_cvt_pk_bf16_f32 v0, v0, v1
	v_cvt_pk_bf16_f32 v1, v2, v3
	v_cvt_pk_bf16_f32 v2, v4, v5
	v_cvt_pk_bf16_f32 v3, v6, v7
	v_cvt_pk_bf16_f32 v4, v8, v9
	v_cvt_pk_bf16_f32 v5, v10, v11
	v_cvt_pk_bf16_f32 v6, v12, v13
	v_cvt_pk_bf16_f32 v7, v14, v15
	s_nop 1
	v_permlane32_swap_b32_e32 v0, v2
	v_permlane32_swap_b32_e32 v1, v3
	v_permlane32_swap_b32_e32 v4, v6
	v_permlane32_swap_b32_e32 v5, v7
	global_store_dwordx4 v[36:37], v[0:3], off
	global_store_dwordx4 v[36:37], v[4:7], off offset:32
	v_pk_mul_f32 v[16:17], v[16:17], v[38:39] op_sel_hi:[1,0]
	v_pk_mul_f32 v[18:19], v[18:19], v[38:39] op_sel_hi:[1,0]
	v_pk_mul_f32 v[20:21], v[20:21], v[38:39] op_sel_hi:[1,0]
	v_pk_mul_f32 v[22:23], v[22:23], v[38:39] op_sel_hi:[1,0]
	v_pk_mul_f32 v[24:25], v[24:25], v[38:39] op_sel_hi:[1,0]
	v_pk_mul_f32 v[26:27], v[26:27], v[38:39] op_sel_hi:[1,0]
	v_pk_mul_f32 v[28:29], v[28:29], v[38:39] op_sel_hi:[1,0]
	v_pk_mul_f32 v[30:31], v[30:31], v[38:39] op_sel_hi:[1,0]
	v_cvt_pk_bf16_f32 v16, v16, v17
	v_cvt_pk_bf16_f32 v17, v18, v19
	v_cvt_pk_bf16_f32 v18, v20, v21
	v_cvt_pk_bf16_f32 v19, v22, v23
	v_cvt_pk_bf16_f32 v20, v24, v25
	v_cvt_pk_bf16_f32 v21, v26, v27
	v_cvt_pk_bf16_f32 v22, v28, v29
	v_cvt_pk_bf16_f32 v23, v30, v31
	s_nop 1
	v_permlane32_swap_b32_e32 v16, v18
	v_permlane32_swap_b32_e32 v17, v19
	v_permlane32_swap_b32_e32 v20, v22
	v_permlane32_swap_b32_e32 v21, v23
	global_store_dwordx4 v[36:37], v[16:19], off offset:64
	global_store_dwordx4 v[36:37], v[20:23], off offset:96
	s_cmpk_gt_i32 s27, 0xbff
	s_cbranch_scc1 .LBB0_305
